# k20 + QK K-fragment reads staggered: first four fragments, then the other four after the first MFMA (smaller LDS burst at segment start)
# speedup vs baseline: 1.0077x; 1.0038x over previous
; #define SBAR() __builtin_amdgcn_sched_barrier(0)
; __device__ __forceinline__ void partialSM(f32x16& p0, f32x16& p1, float& m_reg, float& mn, float& alpha) {
;   constexpr float C = SCALE * 1.4426950408889634f;
;   float pmax = p0[0];
; #pragma unroll
;   for (int r = 1; r < 16; ++r) pmax = fmaxf(pmax, p0[r]);
; #pragma unroll
;   for (int r = 0; r < 16; ++r) pmax = fmaxf(pmax, p1[r]);
;   { auto rr = __builtin_amdgcn_permlane32_swap(__float_as_uint(pmax), __float_as_uint(pmax), false, false);
;     pmax = fmaxf(__uint_as_float(rr[0]), __uint_as_float(rr[1])); }
;   if (__builtin_expect(__all(pmax - m_reg <= THR / SCALE), 1)) { mn = m_reg; alpha = 1.f; }
; template <int OFF> __device__ __forceinline__ bf16x8 k_read(int a) { bf16x8 r; asm volatile("ds_read_b128 %0, %1 offset:%2" : "=&v"(r) : "v"(a), "i"(OFF) : "memory"); return r; }
; template <int BUFOFF, int D0> __device__ __forceinline__ void qk_step(f32x16& p0, f32x16& p1, int ka0, const bf16x8 (&qr)[8], bf16x8 (&k0)[2], bf16x8 (&k1)[2]) {
;   if constexpr (D0 + 1 < 8) { const int a_ = ka0 ^ ((D0 + 1) << 5); k0[(D0 + 1) & 1] = k_read<BUFOFF>(a_); k1[(D0 + 1) & 1] = k_read<BUFOFF + 8192>(a_); }
;   if constexpr (D0 + 1 < 8) asm volatile("s_waitcnt lgkmcnt(2)" ::: "memory"); else asm volatile("s_waitcnt lgkmcnt(0)" ::: "memory");
;   SBAR();
;   p0 = __builtin_amdgcn_mfma_f32_32x32x16_bf16(k0[D0 & 1], qr[D0], p0, 0, 0, 0);
;   p1 = __builtin_amdgcn_mfma_f32_32x32x16_bf16(k1[D0 & 1], qr[D0], p1, 0, 0, 0);
;   SBAR();
;   if constexpr (D0 + 1 < 8) qk_step<BUFOFF, (D0 + 1 < 8 ? D0 + 1 : 7)>(p0, p1, ka0, qr, k0, k1);
; }
; template <int BUFOFF> __device__ __forceinline__ void qkt_rolling(f32x16& p0, f32x16& p1, int ka0, const bf16x8 (&qr)[8]) {
;   bf16x8 k0[2], k1[2];
;   asm volatile("s_waitcnt lgkmcnt(0)" ::: "memory");
;   k0[0] = k_read<BUFOFF>(ka0); k1[0] = k_read<BUFOFF + 8192>(ka0);
;   qk_step<BUFOFF, 0>(p0, p1, ka0, qr, k0, k1);
; }
.LBB0_430:
	s_setprio 1
	v_lshl_add_u64 v[224:225], v[214:215], 0, s[22:23]
	v_lshl_add_u64 v[228:229], v[216:217], 0, s[22:23]
	s_waitcnt lgkmcnt(0)
	ds_read_b128 v[194:197], v235 offset:0
	ds_read_b128 v[198:201], v236 offset:0
	ds_read_b128 v[202:205], v238 offset:0
	ds_read_b128 v[206:209], v239 offset:0
	v_lshl_add_u64 v[232:233], v[224:225], 0, s[10:11]
	s_add_i32 m0, s62, s25
	s_nop 0
	global_load_lds_dwordx4 v[232:233], off
	v_lshl_add_u64 v[232:233], v[228:229], 0, s[10:11]
	s_add_i32 m0, s62, s66
	s_nop 0
	global_load_lds_dwordx4 v[232:233], off
	s_waitcnt lgkmcnt(3)
	s_nop 0
	v_mfma_f32_32x32x16_bf16 v[146:161], v[194:197], v[162:165], 0
	ds_read_b128 v[194:197], v235 offset:8192
	ds_read_b128 v[130:133], v240 offset:0
	ds_read_b128 v[134:137], v241 offset:0
	ds_read_b128 v[138:141], v242 offset:0
	ds_read_b128 v[142:145], v243 offset:0
	s_waitcnt lgkmcnt(7)
	v_mfma_f32_32x32x16_bf16 v[146:161], v[198:201], v[166:169], v[146:161]
	ds_read_b128 v[198:201], v236 offset:8192
	s_waitcnt lgkmcnt(7)
	v_mfma_f32_32x32x16_bf16 v[146:161], v[202:205], v[170:173], v[146:161]
	ds_read_b128 v[202:205], v238 offset:8192
	s_waitcnt lgkmcnt(7)
	v_mfma_f32_32x32x16_bf16 v[146:161], v[206:209], v[174:177], v[146:161]
	ds_read_b128 v[206:209], v239 offset:8192
	s_waitcnt lgkmcnt(6)
	v_mfma_f32_32x32x16_bf16 v[146:161], v[130:133], v[178:181], v[146:161]
	s_waitcnt lgkmcnt(5)
	v_mfma_f32_32x32x16_bf16 v[146:161], v[134:137], v[182:185], v[146:161]
	s_waitcnt lgkmcnt(4)
	v_mfma_f32_32x32x16_bf16 v[146:161], v[138:141], v[186:189], v[146:161]
	s_waitcnt lgkmcnt(3)
	v_mfma_f32_32x32x16_bf16 v[146:161], v[142:145], v[190:193], v[146:161]
	s_waitcnt lgkmcnt(3)
	v_mfma_f32_32x32x16_bf16 v[130:145], v[194:197], v[162:165], 0
	ds_read_b128 v[194:197], v240 offset:8192
	s_waitcnt lgkmcnt(3)
	v_mfma_f32_32x32x16_bf16 v[130:145], v[198:201], v[166:169], v[130:145]
	ds_read_b128 v[198:201], v241 offset:8192
	s_waitcnt lgkmcnt(3)
	v_mfma_f32_32x32x16_bf16 v[130:145], v[202:205], v[170:173], v[130:145]
	ds_read_b128 v[202:205], v242 offset:8192
	s_waitcnt lgkmcnt(3)
	v_mfma_f32_32x32x16_bf16 v[130:145], v[206:209], v[174:177], v[130:145]
	ds_read_b128 v[206:209], v243 offset:8192
	s_waitcnt lgkmcnt(3)
	v_mfma_f32_32x32x16_bf16 v[130:145], v[194:197], v[178:181], v[130:145]
	s_waitcnt lgkmcnt(2)
	v_mfma_f32_32x32x16_bf16 v[130:145], v[198:201], v[182:185], v[130:145]
	s_waitcnt lgkmcnt(1)
	v_mfma_f32_32x32x16_bf16 v[130:145], v[202:205], v[186:189], v[130:145]
	s_waitcnt lgkmcnt(0)
	v_mfma_f32_32x32x16_bf16 v[130:145], v[206:209], v[190:193], v[130:145]
	s_setprio 0
	v_max3_f32 v0, v146, v147, v148
	v_max3_f32 v194, v154, v155, v156
	v_max3_f32 v0, v0, v149, v150
	v_max3_f32 v194, v194, v157, v158
	v_max3_f32 v0, v0, v151, v152
	v_max3_f32 v194, v194, v159, v160
	v_max_f32_e32 v0, v0, v153
	v_max_f32_e32 v194, v194, v161
	s_nop 4
	v_max3_f32 v196, v130, v131, v132
	v_max3_f32 v197, v138, v139, v140
	v_max3_f32 v196, v196, v133, v134
	v_max3_f32 v197, v197, v141, v142
	v_max3_f32 v196, v196, v135, v136
	v_max3_f32 v197, v197, v143, v144
	v_max_f32_e32 v196, v196, v137
	v_max_f32_e32 v197, v197, v145
	v_max3_f32 v0, v0, v194, v196
	v_max_f32_e32 v0, v0, v197
	v_mov_b32_e32 v194, v0
	s_nop 1
	v_permlane32_swap_b32_e32 v0, v194
	v_max_f32_e32 v0, v0, v194
	v_sub_f32_e32 v194, v0, v246
	v_cmp_ge_f32_e32 vcc, s63, v194
	s_cmp_eq_u64 vcc, exec
	s_cbranch_scc0 .Lda_slow_l0_3
	s_mov_b64 s[6:7], -1
	v_mov_b32_e32 v0, 1.0
	s_branch .LBB0_434

; #define SBAR() __builtin_amdgcn_sched_barrier(0)
; __device__ __forceinline__ void partialSM(f32x16& p0, f32x16& p1, float& m_reg, float& mn, float& alpha) {
;   constexpr float C = SCALE * 1.4426950408889634f;
;   float pmax = p0[0];
; #pragma unroll
;   for (int r = 1; r < 16; ++r) pmax = fmaxf(pmax, p0[r]);
; #pragma unroll
;   for (int r = 0; r < 16; ++r) pmax = fmaxf(pmax, p1[r]);
;   { auto rr = __builtin_amdgcn_permlane32_swap(__float_as_uint(pmax), __float_as_uint(pmax), false, false);
;     pmax = fmaxf(__uint_as_float(rr[0]), __uint_as_float(rr[1])); }
;   if (__builtin_expect(__all(pmax - m_reg <= THR / SCALE), 1)) { mn = m_reg; alpha = 1.f; }
; template <int OFF> __device__ __forceinline__ bf16x8 k_read(int a) { bf16x8 r; asm volatile("ds_read_b128 %0, %1 offset:%2" : "=&v"(r) : "v"(a), "i"(OFF) : "memory"); return r; }
; template <int BUFOFF, int D0> __device__ __forceinline__ void qk_step(f32x16& p0, f32x16& p1, int ka0, const bf16x8 (&qr)[8], bf16x8 (&k0)[2], bf16x8 (&k1)[2]) {
;   if constexpr (D0 + 1 < 8) { const int a_ = ka0 ^ ((D0 + 1) << 5); k0[(D0 + 1) & 1] = k_read<BUFOFF>(a_); k1[(D0 + 1) & 1] = k_read<BUFOFF + 8192>(a_); }
;   if constexpr (D0 + 1 < 8) asm volatile("s_waitcnt lgkmcnt(2)" ::: "memory"); else asm volatile("s_waitcnt lgkmcnt(0)" ::: "memory");
;   SBAR();
;   p0 = __builtin_amdgcn_mfma_f32_32x32x16_bf16(k0[D0 & 1], qr[D0], p0, 0, 0, 0);
;   p1 = __builtin_amdgcn_mfma_f32_32x32x16_bf16(k1[D0 & 1], qr[D0], p1, 0, 0, 0);
;   SBAR();
;   if constexpr (D0 + 1 < 8) qk_step<BUFOFF, (D0 + 1 < 8 ? D0 + 1 : 7)>(p0, p1, ka0, qr, k0, k1);
; }
; template <int BUFOFF> __device__ __forceinline__ void qkt_rolling(f32x16& p0, f32x16& p1, int ka0, const bf16x8 (&qr)[8]) {
;   bf16x8 k0[2], k1[2];
;   asm volatile("s_waitcnt lgkmcnt(0)" ::: "memory");
;   k0[0] = k_read<BUFOFF>(ka0); k1[0] = k_read<BUFOFF + 8192>(ka0);
;   qk_step<BUFOFF, 0>(p0, p1, ka0, qr, k0, k1);
; }
.LBB0_436:
	s_setprio 1
	s_waitcnt lgkmcnt(0)
	ds_read_b128 v[194:197], v235 offset:16384
	ds_read_b128 v[198:201], v236 offset:16384
	ds_read_b128 v[202:205], v238 offset:16384
	ds_read_b128 v[206:209], v239 offset:16384
	v_lshl_add_u64 v[232:233], v[224:225], 0, s[14:15]
	s_mov_b32 m0, s28
	s_nop 0
	global_load_lds_dwordx4 v[232:233], off
	v_lshl_add_u64 v[232:233], v[228:229], 0, s[14:15]
	s_mov_b32 m0, s67
	s_nop 0
	global_load_lds_dwordx4 v[232:233], off
	s_waitcnt lgkmcnt(3)
	s_nop 0
	v_mfma_f32_32x32x16_bf16 v[146:161], v[194:197], v[162:165], 0
	ds_read_b128 v[194:197], v235 offset:24576
	ds_read_b128 v[130:133], v240 offset:16384
	ds_read_b128 v[134:137], v241 offset:16384
	ds_read_b128 v[138:141], v242 offset:16384
	ds_read_b128 v[142:145], v243 offset:16384
	s_waitcnt lgkmcnt(7)
	v_mfma_f32_32x32x16_bf16 v[146:161], v[198:201], v[166:169], v[146:161]
	ds_read_b128 v[198:201], v236 offset:24576
	s_waitcnt lgkmcnt(7)
	v_mfma_f32_32x32x16_bf16 v[146:161], v[202:205], v[170:173], v[146:161]
	ds_read_b128 v[202:205], v238 offset:24576
	s_waitcnt lgkmcnt(7)
	v_mfma_f32_32x32x16_bf16 v[146:161], v[206:209], v[174:177], v[146:161]
	ds_read_b128 v[206:209], v239 offset:24576
	s_waitcnt lgkmcnt(6)
	v_mfma_f32_32x32x16_bf16 v[146:161], v[130:133], v[178:181], v[146:161]
	s_waitcnt lgkmcnt(5)
	v_mfma_f32_32x32x16_bf16 v[146:161], v[134:137], v[182:185], v[146:161]
	s_waitcnt lgkmcnt(4)
	v_mfma_f32_32x32x16_bf16 v[146:161], v[138:141], v[186:189], v[146:161]
	s_waitcnt lgkmcnt(3)
	v_mfma_f32_32x32x16_bf16 v[146:161], v[142:145], v[190:193], v[146:161]
	s_waitcnt lgkmcnt(3)
	v_mfma_f32_32x32x16_bf16 v[130:145], v[194:197], v[162:165], 0
	ds_read_b128 v[194:197], v240 offset:24576
	s_waitcnt lgkmcnt(3)
	v_mfma_f32_32x32x16_bf16 v[130:145], v[198:201], v[166:169], v[130:145]
	ds_read_b128 v[198:201], v241 offset:24576
	s_waitcnt lgkmcnt(3)
	v_mfma_f32_32x32x16_bf16 v[130:145], v[202:205], v[170:173], v[130:145]
	ds_read_b128 v[202:205], v242 offset:24576
	s_waitcnt lgkmcnt(3)
	v_mfma_f32_32x32x16_bf16 v[130:145], v[206:209], v[174:177], v[130:145]
	ds_read_b128 v[206:209], v243 offset:24576
	s_waitcnt lgkmcnt(3)
	v_mfma_f32_32x32x16_bf16 v[130:145], v[194:197], v[178:181], v[130:145]
	s_waitcnt lgkmcnt(2)
	v_mfma_f32_32x32x16_bf16 v[130:145], v[198:201], v[182:185], v[130:145]
	s_waitcnt lgkmcnt(1)
	v_mfma_f32_32x32x16_bf16 v[130:145], v[202:205], v[186:189], v[130:145]
	s_waitcnt lgkmcnt(0)
	v_mfma_f32_32x32x16_bf16 v[130:145], v[206:209], v[190:193], v[130:145]
	s_setprio 0
	v_max3_f32 v194, v146, v147, v148
	v_max3_f32 v195, v154, v155, v156
	v_max3_f32 v194, v194, v149, v150
	v_max3_f32 v195, v195, v157, v158
	v_max3_f32 v194, v194, v151, v152
	v_max3_f32 v195, v195, v159, v160
	v_max_f32_e32 v194, v194, v153
	v_max_f32_e32 v195, v195, v161
	s_nop 4
	v_max3_f32 v196, v130, v131, v132
	v_max3_f32 v197, v138, v139, v140
	v_max3_f32 v196, v196, v133, v134
	v_max3_f32 v197, v197, v141, v142
	v_max3_f32 v196, v196, v135, v136
	v_max3_f32 v197, v197, v143, v144
	v_max_f32_e32 v196, v196, v137
	v_max_f32_e32 v197, v197, v145
	v_max3_f32 v194, v194, v195, v196
	v_max_f32_e32 v194, v194, v197
	v_mov_b32_e32 v195, v194
	s_nop 1
	v_permlane32_swap_b32_e32 v194, v195
	v_max_f32_e32 v194, v194, v195
	v_sub_f32_e32 v195, v194, v246
	v_cmp_ge_f32_e32 vcc, s63, v195
	s_cmp_eq_u64 vcc, exec
	s_cbranch_scc0 .Lda_slow_l0_4
	s_mov_b64 s[6:7], -1
	v_mov_b32_e32 v222, 1.0
	s_branch .LBB0_429

; #define SBAR() __builtin_amdgcn_sched_barrier(0)
; __device__ __forceinline__ void partialSM(f32x16& p0, f32x16& p1, float& m_reg, float& mn, float& alpha) {
;   constexpr float C = SCALE * 1.4426950408889634f;
;   float pmax = p0[0];
; #pragma unroll
;   for (int r = 1; r < 16; ++r) pmax = fmaxf(pmax, p0[r]);
; #pragma unroll
;   for (int r = 0; r < 16; ++r) pmax = fmaxf(pmax, p1[r]);
;   { auto rr = __builtin_amdgcn_permlane32_swap(__float_as_uint(pmax), __float_as_uint(pmax), false, false);
;     pmax = fmaxf(__uint_as_float(rr[0]), __uint_as_float(rr[1])); }
;   if (__builtin_expect(__all(pmax - m_reg <= THR / SCALE), 1)) { mn = m_reg; alpha = 1.f; }
; template <int OFF> __device__ __forceinline__ bf16x8 k_read(int a) { bf16x8 r; asm volatile("ds_read_b128 %0, %1 offset:%2" : "=&v"(r) : "v"(a), "i"(OFF) : "memory"); return r; }
; template <int BUFOFF, int D0> __device__ __forceinline__ void qk_step(f32x16& p0, f32x16& p1, int ka0, const bf16x8 (&qr)[8], bf16x8 (&k0)[2], bf16x8 (&k1)[2]) {
;   if constexpr (D0 + 1 < 8) { const int a_ = ka0 ^ ((D0 + 1) << 5); k0[(D0 + 1) & 1] = k_read<BUFOFF>(a_); k1[(D0 + 1) & 1] = k_read<BUFOFF + 8192>(a_); }
;   if constexpr (D0 + 1 < 8) asm volatile("s_waitcnt lgkmcnt(2)" ::: "memory"); else asm volatile("s_waitcnt lgkmcnt(0)" ::: "memory");
;   SBAR();
;   p0 = __builtin_amdgcn_mfma_f32_32x32x16_bf16(k0[D0 & 1], qr[D0], p0, 0, 0, 0);
;   p1 = __builtin_amdgcn_mfma_f32_32x32x16_bf16(k1[D0 & 1], qr[D0], p1, 0, 0, 0);
;   SBAR();
;   if constexpr (D0 + 1 < 8) qk_step<BUFOFF, (D0 + 1 < 8 ? D0 + 1 : 7)>(p0, p1, ka0, qr, k0, k1);
; }
; template <int BUFOFF> __device__ __forceinline__ void qkt_rolling(f32x16& p0, f32x16& p1, int ka0, const bf16x8 (&qr)[8]) {
;   bf16x8 k0[2], k1[2];
;   asm volatile("s_waitcnt lgkmcnt(0)" ::: "memory");
;   k0[0] = k_read<BUFOFF>(ka0); k1[0] = k_read<BUFOFF + 8192>(ka0);
;   qk_step<BUFOFF, 0>(p0, p1, ka0, qr, k0, k1);
; }
.LBB0_1436:
	s_setprio 1
	v_lshl_add_u64 v[224:225], v[214:215], 0, s[22:23]
	v_lshl_add_u64 v[228:229], v[216:217], 0, s[22:23]
	s_waitcnt lgkmcnt(0)
	ds_read_b128 v[194:197], v235 offset:0
	ds_read_b128 v[198:201], v236 offset:0
	ds_read_b128 v[202:205], v238 offset:0
	ds_read_b128 v[206:209], v239 offset:0
	v_lshl_add_u64 v[232:233], v[224:225], 0, s[10:11]
	s_add_i32 m0, s94, s29
	s_nop 0
	global_load_lds_dwordx4 v[232:233], off
	v_lshl_add_u64 v[232:233], v[228:229], 0, s[10:11]
	s_add_i32 m0, s94, s66
	s_nop 0
	global_load_lds_dwordx4 v[232:233], off
	s_waitcnt lgkmcnt(3)
	s_nop 0
	v_mfma_f32_32x32x16_bf16 v[146:161], v[194:197], v[162:165], 0
	ds_read_b128 v[194:197], v235 offset:8192
	ds_read_b128 v[130:133], v240 offset:0
	ds_read_b128 v[134:137], v241 offset:0
	ds_read_b128 v[138:141], v242 offset:0
	ds_read_b128 v[142:145], v243 offset:0
	s_waitcnt lgkmcnt(7)
	v_mfma_f32_32x32x16_bf16 v[146:161], v[198:201], v[166:169], v[146:161]
	ds_read_b128 v[198:201], v236 offset:8192
	s_waitcnt lgkmcnt(7)
	v_mfma_f32_32x32x16_bf16 v[146:161], v[202:205], v[170:173], v[146:161]
	ds_read_b128 v[202:205], v238 offset:8192
	s_waitcnt lgkmcnt(7)
	v_mfma_f32_32x32x16_bf16 v[146:161], v[206:209], v[174:177], v[146:161]
	ds_read_b128 v[206:209], v239 offset:8192
	s_waitcnt lgkmcnt(6)
	v_mfma_f32_32x32x16_bf16 v[146:161], v[130:133], v[178:181], v[146:161]
	s_waitcnt lgkmcnt(5)
	v_mfma_f32_32x32x16_bf16 v[146:161], v[134:137], v[182:185], v[146:161]
	s_waitcnt lgkmcnt(4)
	v_mfma_f32_32x32x16_bf16 v[146:161], v[138:141], v[186:189], v[146:161]
	s_waitcnt lgkmcnt(3)
	v_mfma_f32_32x32x16_bf16 v[146:161], v[142:145], v[190:193], v[146:161]
	s_waitcnt lgkmcnt(3)
	v_mfma_f32_32x32x16_bf16 v[130:145], v[194:197], v[162:165], 0
	ds_read_b128 v[194:197], v240 offset:8192
	s_waitcnt lgkmcnt(3)
	v_mfma_f32_32x32x16_bf16 v[130:145], v[198:201], v[166:169], v[130:145]
	ds_read_b128 v[198:201], v241 offset:8192
	s_waitcnt lgkmcnt(3)
	v_mfma_f32_32x32x16_bf16 v[130:145], v[202:205], v[170:173], v[130:145]
	ds_read_b128 v[202:205], v242 offset:8192
	s_waitcnt lgkmcnt(3)
	v_mfma_f32_32x32x16_bf16 v[130:145], v[206:209], v[174:177], v[130:145]
	ds_read_b128 v[206:209], v243 offset:8192
	s_waitcnt lgkmcnt(3)
	v_mfma_f32_32x32x16_bf16 v[130:145], v[194:197], v[178:181], v[130:145]
	s_waitcnt lgkmcnt(2)
	v_mfma_f32_32x32x16_bf16 v[130:145], v[198:201], v[182:185], v[130:145]
	s_waitcnt lgkmcnt(1)
	v_mfma_f32_32x32x16_bf16 v[130:145], v[202:205], v[186:189], v[130:145]
	s_waitcnt lgkmcnt(0)
	v_mfma_f32_32x32x16_bf16 v[130:145], v[206:209], v[190:193], v[130:145]
	s_setprio 0
	v_max3_f32 v0, v146, v147, v148
	v_max3_f32 v194, v154, v155, v156
	v_max3_f32 v0, v0, v149, v150
	v_max3_f32 v194, v194, v157, v158
	v_max3_f32 v0, v0, v151, v152
	v_max3_f32 v194, v194, v159, v160
	v_max_f32_e32 v0, v0, v153
	v_max_f32_e32 v194, v194, v161
	s_nop 4
	v_max3_f32 v196, v130, v131, v132
	v_max3_f32 v197, v138, v139, v140
	v_max3_f32 v196, v196, v133, v134
	v_max3_f32 v197, v197, v141, v142
	v_max3_f32 v196, v196, v135, v136
	v_max3_f32 v197, v197, v143, v144
	v_max_f32_e32 v196, v196, v137
	v_max_f32_e32 v197, v197, v145
	v_max3_f32 v0, v0, v194, v196
	v_max_f32_e32 v0, v0, v197
	v_mov_b32_e32 v194, v0
	s_nop 1
	v_permlane32_swap_b32_e32 v0, v194
	v_max_f32_e32 v0, v0, v194
	v_sub_f32_e32 v194, v0, v246
	v_cmp_ge_f32_e32 vcc, s95, v194
	s_cmp_eq_u64 vcc, exec
	s_cbranch_scc0 .Lda_slow_l1_1
	s_mov_b64 s[6:7], -1
	v_mov_b32_e32 v0, 1.0
	s_branch .LBB0_1440

; #define SBAR() __builtin_amdgcn_sched_barrier(0)
; __device__ __forceinline__ void partialSM(f32x16& p0, f32x16& p1, float& m_reg, float& mn, float& alpha) {
;   constexpr float C = SCALE * 1.4426950408889634f;
;   float pmax = p0[0];
; #pragma unroll
;   for (int r = 1; r < 16; ++r) pmax = fmaxf(pmax, p0[r]);
; #pragma unroll
;   for (int r = 0; r < 16; ++r) pmax = fmaxf(pmax, p1[r]);
;   { auto rr = __builtin_amdgcn_permlane32_swap(__float_as_uint(pmax), __float_as_uint(pmax), false, false);
;     pmax = fmaxf(__uint_as_float(rr[0]), __uint_as_float(rr[1])); }
;   if (__builtin_expect(__all(pmax - m_reg <= THR / SCALE), 1)) { mn = m_reg; alpha = 1.f; }
; template <int OFF> __device__ __forceinline__ bf16x8 k_read(int a) { bf16x8 r; asm volatile("ds_read_b128 %0, %1 offset:%2" : "=&v"(r) : "v"(a), "i"(OFF) : "memory"); return r; }
; template <int BUFOFF, int D0> __device__ __forceinline__ void qk_step(f32x16& p0, f32x16& p1, int ka0, const bf16x8 (&qr)[8], bf16x8 (&k0)[2], bf16x8 (&k1)[2]) {
;   if constexpr (D0 + 1 < 8) { const int a_ = ka0 ^ ((D0 + 1) << 5); k0[(D0 + 1) & 1] = k_read<BUFOFF>(a_); k1[(D0 + 1) & 1] = k_read<BUFOFF + 8192>(a_); }
;   if constexpr (D0 + 1 < 8) asm volatile("s_waitcnt lgkmcnt(2)" ::: "memory"); else asm volatile("s_waitcnt lgkmcnt(0)" ::: "memory");
;   SBAR();
;   p0 = __builtin_amdgcn_mfma_f32_32x32x16_bf16(k0[D0 & 1], qr[D0], p0, 0, 0, 0);
;   p1 = __builtin_amdgcn_mfma_f32_32x32x16_bf16(k1[D0 & 1], qr[D0], p1, 0, 0, 0);
;   SBAR();
;   if constexpr (D0 + 1 < 8) qk_step<BUFOFF, (D0 + 1 < 8 ? D0 + 1 : 7)>(p0, p1, ka0, qr, k0, k1);
; }
; template <int BUFOFF> __device__ __forceinline__ void qkt_rolling(f32x16& p0, f32x16& p1, int ka0, const bf16x8 (&qr)[8]) {
;   bf16x8 k0[2], k1[2];
;   asm volatile("s_waitcnt lgkmcnt(0)" ::: "memory");
;   k0[0] = k_read<BUFOFF>(ka0); k1[0] = k_read<BUFOFF + 8192>(ka0);
;   qk_step<BUFOFF, 0>(p0, p1, ka0, qr, k0, k1);
; }
.LBB0_1442:
	s_setprio 1
	s_waitcnt lgkmcnt(0)
	ds_read_b128 v[194:197], v235 offset:16384
	ds_read_b128 v[198:201], v236 offset:16384
	ds_read_b128 v[202:205], v238 offset:16384
	ds_read_b128 v[206:209], v239 offset:16384
	v_lshl_add_u64 v[232:233], v[224:225], 0, s[14:15]
	s_mov_b32 m0, s61
	s_nop 0
	global_load_lds_dwordx4 v[232:233], off
	v_lshl_add_u64 v[232:233], v[228:229], 0, s[14:15]
	s_mov_b32 m0, s67
	s_nop 0
	global_load_lds_dwordx4 v[232:233], off
	s_waitcnt lgkmcnt(3)
	s_nop 0
	v_mfma_f32_32x32x16_bf16 v[146:161], v[194:197], v[162:165], 0
	ds_read_b128 v[194:197], v235 offset:24576
	ds_read_b128 v[130:133], v240 offset:16384
	ds_read_b128 v[134:137], v241 offset:16384
	ds_read_b128 v[138:141], v242 offset:16384
	ds_read_b128 v[142:145], v243 offset:16384
	s_waitcnt lgkmcnt(7)
	v_mfma_f32_32x32x16_bf16 v[146:161], v[198:201], v[166:169], v[146:161]
	ds_read_b128 v[198:201], v236 offset:24576
	s_waitcnt lgkmcnt(7)
	v_mfma_f32_32x32x16_bf16 v[146:161], v[202:205], v[170:173], v[146:161]
	ds_read_b128 v[202:205], v238 offset:24576
	s_waitcnt lgkmcnt(7)
	v_mfma_f32_32x32x16_bf16 v[146:161], v[206:209], v[174:177], v[146:161]
	ds_read_b128 v[206:209], v239 offset:24576
	s_waitcnt lgkmcnt(6)
	v_mfma_f32_32x32x16_bf16 v[146:161], v[130:133], v[178:181], v[146:161]
	s_waitcnt lgkmcnt(5)
	v_mfma_f32_32x32x16_bf16 v[146:161], v[134:137], v[182:185], v[146:161]
	s_waitcnt lgkmcnt(4)
	v_mfma_f32_32x32x16_bf16 v[146:161], v[138:141], v[186:189], v[146:161]
	s_waitcnt lgkmcnt(3)
	v_mfma_f32_32x32x16_bf16 v[146:161], v[142:145], v[190:193], v[146:161]
	s_waitcnt lgkmcnt(3)
	v_mfma_f32_32x32x16_bf16 v[130:145], v[194:197], v[162:165], 0
	ds_read_b128 v[194:197], v240 offset:24576
	s_waitcnt lgkmcnt(3)
	v_mfma_f32_32x32x16_bf16 v[130:145], v[198:201], v[166:169], v[130:145]
	ds_read_b128 v[198:201], v241 offset:24576
	s_waitcnt lgkmcnt(3)
	v_mfma_f32_32x32x16_bf16 v[130:145], v[202:205], v[170:173], v[130:145]
	ds_read_b128 v[202:205], v242 offset:24576
	s_waitcnt lgkmcnt(3)
	v_mfma_f32_32x32x16_bf16 v[130:145], v[206:209], v[174:177], v[130:145]
	ds_read_b128 v[206:209], v243 offset:24576
	s_waitcnt lgkmcnt(3)
	v_mfma_f32_32x32x16_bf16 v[130:145], v[194:197], v[178:181], v[130:145]
	s_waitcnt lgkmcnt(2)
	v_mfma_f32_32x32x16_bf16 v[130:145], v[198:201], v[182:185], v[130:145]
	s_waitcnt lgkmcnt(1)
	v_mfma_f32_32x32x16_bf16 v[130:145], v[202:205], v[186:189], v[130:145]
	s_waitcnt lgkmcnt(0)
	v_mfma_f32_32x32x16_bf16 v[130:145], v[206:209], v[190:193], v[130:145]
	s_setprio 0
	v_max3_f32 v194, v146, v147, v148
	v_max3_f32 v195, v154, v155, v156
	v_max3_f32 v194, v194, v149, v150
	v_max3_f32 v195, v195, v157, v158
	v_max3_f32 v194, v194, v151, v152
	v_max3_f32 v195, v195, v159, v160
	v_max_f32_e32 v194, v194, v153
	v_max_f32_e32 v195, v195, v161
	s_nop 4
	v_max3_f32 v196, v130, v131, v132
	v_max3_f32 v197, v138, v139, v140
	v_max3_f32 v196, v196, v133, v134
	v_max3_f32 v197, v197, v141, v142
	v_max3_f32 v196, v196, v135, v136
	v_max3_f32 v197, v197, v143, v144
	v_max_f32_e32 v196, v196, v137
	v_max_f32_e32 v197, v197, v145
	v_max3_f32 v194, v194, v195, v196
	v_max_f32_e32 v194, v194, v197
	v_mov_b32_e32 v195, v194
	s_nop 1
	v_permlane32_swap_b32_e32 v194, v195
	v_max_f32_e32 v194, v194, v195
	v_sub_f32_e32 v195, v194, v246
	v_cmp_ge_f32_e32 vcc, s95, v195
	s_cmp_eq_u64 vcc, exec
	s_cbranch_scc0 .Lda_slow_l1_2
	s_mov_b64 s[6:7], -1
	v_mov_b32_e32 v222, 1.0
	s_branch .LBB0_1435
